# prologue: second-round modulation items moved to the workgroups with the least weight-conversion work
# speedup vs baseline: 1.0009x; 1.0009x over previous
.LBB0_408:
	v_add_u32_e32 v89, s24, v51
	ds_read_b128 v[0:3], v89
	ds_read_b128 v[8:11], v89 offset:16
	ds_read_b128 v[76:79], v89 offset:28672
	ds_read_b128 v[22:25], v89 offset:4096
	ds_read_b128 v[30:33], v89 offset:4112
	ds_read_b128 v[38:41], v89 offset:8192
	ds_read_b128 v[12:15], v89 offset:8208
	ds_read_b128 v[34:37], v89 offset:12288
	ds_read_b128 v[26:29], v89 offset:12304
	ds_read_b128 v[42:45], v89 offset:16384
	ds_read_b128 v[18:21], v89 offset:16400
	ds_read_b128 v[46:49], v89 offset:20480
	ds_read_b128 v[4:7], v89 offset:20496
	s_waitcnt lgkmcnt(9)
	v_mov_b32_e32 v72, v22
	v_mov_b32_e32 v73, v0
	v_mov_b32_e32 v0, v23
	v_mov_b32_e32 v64, v24
	v_mov_b32_e32 v65, v2
	v_mov_b32_e32 v2, v25
	s_waitcnt lgkmcnt(5)
	v_mov_b32_e32 v74, v34
	v_mov_b32_e32 v75, v38
	v_mov_b32_e32 v38, v35
	v_mov_b32_e32 v66, v36
	v_mov_b32_e32 v67, v40
	v_mov_b32_e32 v40, v37
	s_waitcnt lgkmcnt(1)
	v_mov_b32_e32 v80, v46
	v_mov_b32_e32 v81, v42
	v_mov_b32_e32 v42, v47
	v_mov_b32_e32 v68, v48
	v_mov_b32_e32 v69, v44
	v_mov_b32_e32 v44, v49
	ds_read_b128 v[34:37], v89 offset:28688
	v_mov_b32_e32 v82, v76
	ds_read_b128 v[46:49], v89 offset:24576
	ds_read_b128 v[22:25], v89 offset:24592
	global_load_dword v76, v[56:57], off
	v_mov_b32_e32 v70, v78
	s_add_i32 s24, s24, 64
	s_waitcnt lgkmcnt(1)
	v_mov_b32_e32 v83, v46
	v_mov_b32_e32 v46, v77
	v_mov_b32_e32 v71, v48
	v_mov_b32_e32 v48, v79
	s_cmpk_eq_i32 s24, 0x200
	s_waitcnt vmcnt(0)
	v_pk_fma_f32 v[62:63], v[76:77], v[72:73], v[62:63] op_sel_hi:[0,1,1]
	v_lshl_add_u64 v[72:73], v[56:57], 0, s[44:45]
	v_pk_fma_f32 v[60:61], v[76:77], v[74:75], v[60:61] op_sel_hi:[0,1,1]
	global_load_dword v74, v[72:73], off
	v_lshl_add_u64 v[72:73], v[72:73], 0, s[44:45]
	v_pk_fma_f32 v[58:59], v[76:77], v[80:81], v[58:59] op_sel_hi:[0,1,1]
	v_pk_fma_f32 v[16:17], v[76:77], v[82:83], v[16:17] op_sel_hi:[0,1,1]
	global_load_dword v76, v[72:73], off
	v_lshl_add_u64 v[72:73], v[72:73], 0, s[44:45]
	global_load_dword v78, v[72:73], off
	v_lshl_add_u64 v[72:73], v[72:73], 0, s[44:45]
	global_load_dword v80, v[72:73], off
	v_lshl_add_u64 v[72:73], v[72:73], 0, s[44:45]
	global_load_dword v82, v[72:73], off
	v_lshl_add_u64 v[72:73], v[72:73], 0, s[44:45]
	global_load_dword v84, v[72:73], off
	v_lshl_add_u64 v[72:73], v[72:73], 0, s[44:45]
	global_load_dword v86, v[72:73], off
	v_lshl_add_u64 v[72:73], v[72:73], 0, s[44:45]
	global_load_dword v88, v[72:73], off
	v_lshl_add_u64 v[56:57], v[56:57], 0, s[70:71]
	s_waitcnt vmcnt(7)
	v_pk_fma_f32 v[38:39], v[74:75], v[38:39], v[60:61] op_sel_hi:[0,1,1]
	v_pk_fma_f32 v[42:43], v[74:75], v[42:43], v[58:59] op_sel_hi:[0,1,1]
	v_pk_fma_f32 v[16:17], v[74:75], v[46:47], v[16:17] op_sel_hi:[0,1,1]
	v_pk_fma_f32 v[0:1], v[74:75], v[0:1], v[62:63] op_sel_hi:[0,1,1]
	s_waitcnt vmcnt(6)
	v_pk_fma_f32 v[38:39], v[76:77], v[66:67], v[38:39] op_sel_hi:[0,1,1]
	v_pk_fma_f32 v[42:43], v[76:77], v[68:69], v[42:43] op_sel_hi:[0,1,1]
	v_pk_fma_f32 v[16:17], v[76:77], v[70:71], v[16:17] op_sel_hi:[0,1,1]
	s_waitcnt vmcnt(5)
	v_pk_fma_f32 v[38:39], v[78:79], v[40:41], v[38:39] op_sel_hi:[0,1,1]
	v_pk_fma_f32 v[40:41], v[78:79], v[44:45], v[42:43] op_sel_hi:[0,1,1]
	v_mov_b32_e32 v42, v30
	v_mov_b32_e32 v43, v8
	v_mov_b32_e32 v8, v31
	v_mov_b32_e32 v44, v32
	v_mov_b32_e32 v45, v10
	v_mov_b32_e32 v10, v33
	v_mov_b32_e32 v30, v26
	v_mov_b32_e32 v31, v12
	v_mov_b32_e32 v32, v4
	v_mov_b32_e32 v33, v18
	v_pk_fma_f32 v[0:1], v[76:77], v[64:65], v[0:1] op_sel_hi:[0,1,1]
	ds_read_b128 v[60:63], v89 offset:32
	v_pk_fma_f32 v[16:17], v[78:79], v[48:49], v[16:17] op_sel_hi:[0,1,1]
	v_mov_b32_e32 v12, v27
	v_mov_b32_e32 v48, v28
	v_mov_b32_e32 v49, v14
	v_mov_b32_e32 v14, v29
	v_mov_b32_e32 v18, v5
	v_mov_b32_e32 v58, v6
	v_mov_b32_e32 v59, v20
	v_mov_b32_e32 v20, v7
	v_mov_b32_e32 v66, v36
	s_waitcnt lgkmcnt(1)
	v_mov_b32_e32 v67, v24
	v_mov_b32_e32 v24, v37
	ds_read_b128 v[26:29], v89 offset:4128
	s_waitcnt vmcnt(4)
	v_pk_fma_f32 v[36:37], v[80:81], v[30:31], v[38:39] op_sel_hi:[0,1,1]
	ds_read_b128 v[4:7], v89 offset:8224
	v_pk_fma_f32 v[38:39], v[80:81], v[32:33], v[40:41] op_sel_hi:[0,1,1]
	ds_read_b128 v[30:33], v89 offset:12320
	v_pk_fma_f32 v[46:47], v[78:79], v[2:3], v[0:1] op_sel_hi:[0,1,1]
	v_mov_b32_e32 v64, v34
	v_mov_b32_e32 v65, v22
	v_mov_b32_e32 v22, v35
	v_pk_fma_f32 v[34:35], v[80:81], v[42:43], v[46:47] op_sel_hi:[0,1,1]
	v_pk_fma_f32 v[16:17], v[80:81], v[64:65], v[16:17] op_sel_hi:[0,1,1]
	s_waitcnt vmcnt(3)
	v_pk_fma_f32 v[8:9], v[82:83], v[8:9], v[34:35] op_sel_hi:[0,1,1]
	v_pk_fma_f32 v[12:13], v[82:83], v[12:13], v[36:37] op_sel_hi:[0,1,1]
	v_pk_fma_f32 v[38:39], v[82:83], v[18:19], v[38:39] op_sel_hi:[0,1,1]
	v_pk_fma_f32 v[22:23], v[82:83], v[22:23], v[16:17] op_sel_hi:[0,1,1]
	s_waitcnt vmcnt(2)
	v_pk_fma_f32 v[8:9], v[84:85], v[44:45], v[8:9] op_sel_hi:[0,1,1]
	v_pk_fma_f32 v[12:13], v[84:85], v[48:49], v[12:13] op_sel_hi:[0,1,1]
	v_pk_fma_f32 v[46:47], v[84:85], v[58:59], v[38:39] op_sel_hi:[0,1,1]
	v_pk_fma_f32 v[22:23], v[84:85], v[66:67], v[22:23] op_sel_hi:[0,1,1]
	ds_read_b128 v[0:3], v89 offset:48
	ds_read_b128 v[16:19], v89 offset:16416
	ds_read_b128 v[34:37], v89 offset:20512
	ds_read_b128 v[38:41], v89 offset:4144
	s_waitcnt vmcnt(1)
	v_pk_fma_f32 v[58:59], v[86:87], v[10:11], v[8:9] op_sel_hi:[0,1,1]
	ds_read_b128 v[8:11], v89 offset:8240
	v_pk_fma_f32 v[68:69], v[86:87], v[14:15], v[12:13] op_sel_hi:[0,1,1]
	ds_read_b128 v[42:45], v89 offset:12336
	v_pk_fma_f32 v[70:71], v[86:87], v[20:21], v[46:47] op_sel_hi:[0,1,1]
	ds_read_b128 v[12:15], v89 offset:16432
	v_pk_fma_f32 v[74:75], v[86:87], v[24:25], v[22:23] op_sel_hi:[0,1,1]
	ds_read_b128 v[46:49], v89 offset:20528
	s_waitcnt lgkmcnt(10)
	v_mov_b32_e32 v76, v26
	v_mov_b32_e32 v77, v60
	v_mov_b32_e32 v60, v27
	v_mov_b32_e32 v78, v28
	v_mov_b32_e32 v79, v62
	v_mov_b32_e32 v62, v29
	s_waitcnt lgkmcnt(8)
	v_mov_b32_e32 v80, v30
	v_mov_b32_e32 v81, v4
	v_mov_b32_e32 v4, v31
	ds_read_b128 v[28:31], v89 offset:28704
	ds_read_b128 v[64:67], v89 offset:28720
	ds_read_b128 v[24:27], v89 offset:24608
	ds_read_b128 v[20:23], v89 offset:24624
	s_waitcnt lgkmcnt(9)
	v_mov_b32_e32 v86, v36
	v_mov_b32_e32 v87, v18
	v_mov_b32_e32 v18, v37
	s_waitcnt lgkmcnt(6)
	v_mov_b32_e32 v36, v42
	v_mov_b32_e32 v37, v8
	v_mov_b32_e32 v8, v43
	s_waitcnt lgkmcnt(2)
	v_mov_b32_e32 v42, v64
	s_waitcnt lgkmcnt(0)
	v_mov_b32_e32 v43, v20
	v_mov_b32_e32 v20, v65
	v_lshl_add_u64 v[64:65], v[72:73], 0, s[44:45]
	v_mov_b32_e32 v82, v32
	v_mov_b32_e32 v32, v38
	v_mov_b32_e32 v38, v66
	global_load_dword v66, v[64:65], off
	v_lshl_add_u64 v[64:65], v[64:65], 0, s[44:45]
	v_mov_b32_e32 v90, v28
	v_mov_b32_e32 v91, v24
	v_mov_b32_e32 v24, v29
	v_mov_b32_e32 v28, v40
	v_mov_b32_e32 v29, v2
	v_mov_b32_e32 v2, v41
	v_mov_b32_e32 v40, v46
	v_mov_b32_e32 v41, v12
	v_mov_b32_e32 v12, v47
	s_waitcnt vmcnt(1)
	v_pk_fma_f32 v[46:47], v[88:89], v[80:81], v[68:69] op_sel_hi:[0,1,1]
	global_load_dword v68, v[64:65], off
	v_mov_b32_e32 v84, v34
	v_mov_b32_e32 v85, v16
	v_mov_b32_e32 v92, v30
	v_mov_b32_e32 v93, v26
	v_mov_b32_e32 v26, v31
	v_mov_b32_e32 v30, v44
	v_mov_b32_e32 v31, v10
	v_mov_b32_e32 v10, v45
	v_pk_fma_f32 v[44:45], v[88:89], v[76:77], v[58:59] op_sel_hi:[0,1,1]
	v_mov_b32_e32 v83, v6
	v_mov_b32_e32 v16, v35
	v_mov_b32_e32 v34, v48
	v_mov_b32_e32 v35, v14
	v_mov_b32_e32 v14, v49
	v_pk_fma_f32 v[48:49], v[88:89], v[84:85], v[70:71] op_sel_hi:[0,1,1]
	v_pk_fma_f32 v[58:59], v[88:89], v[90:91], v[74:75] op_sel_hi:[0,1,1]
	v_mov_b32_e32 v6, v33
	v_mov_b32_e32 v33, v0
	v_mov_b32_e32 v0, v39
	v_mov_b32_e32 v39, v22
	v_mov_b32_e32 v22, v67
	s_waitcnt vmcnt(1)
	v_pk_fma_f32 v[44:45], v[66:67], v[60:61], v[44:45] op_sel_hi:[0,1,1]
	v_pk_fma_f32 v[4:5], v[66:67], v[4:5], v[46:47] op_sel_hi:[0,1,1]
	v_pk_fma_f32 v[16:17], v[66:67], v[16:17], v[48:49] op_sel_hi:[0,1,1]
	v_pk_fma_f32 v[24:25], v[66:67], v[24:25], v[58:59] op_sel_hi:[0,1,1]
	s_waitcnt vmcnt(0)
	v_pk_fma_f32 v[66:67], v[68:69], v[78:79], v[44:45] op_sel_hi:[0,1,1]
	v_pk_fma_f32 v[44:45], v[68:69], v[82:83], v[4:5] op_sel_hi:[0,1,1]
	v_lshl_add_u64 v[4:5], v[64:65], 0, s[44:45]
	global_load_dword v58, v[4:5], off
	v_lshl_add_u64 v[4:5], v[4:5], 0, s[44:45]
	global_load_dword v46, v[4:5], off
	v_lshl_add_u64 v[4:5], v[4:5], 0, s[44:45]
	v_pk_fma_f32 v[60:61], v[68:69], v[92:93], v[24:25] op_sel_hi:[0,1,1]
	global_load_dword v24, v[4:5], off
	v_lshl_add_u64 v[4:5], v[4:5], 0, s[44:45]
	v_pk_fma_f32 v[48:49], v[68:69], v[86:87], v[16:17] op_sel_hi:[0,1,1]
	global_load_dword v16, v[4:5], off
	v_lshl_add_u64 v[4:5], v[4:5], 0, s[44:45]
	global_load_dword v4, v[4:5], off
	s_waitcnt vmcnt(4)
	v_pk_fma_f32 v[62:63], v[58:59], v[62:63], v[66:67] op_sel_hi:[0,1,1]
	v_pk_fma_f32 v[6:7], v[58:59], v[6:7], v[44:45] op_sel_hi:[0,1,1]
	v_pk_fma_f32 v[18:19], v[58:59], v[18:19], v[48:49] op_sel_hi:[0,1,1]
	v_pk_fma_f32 v[26:27], v[58:59], v[26:27], v[60:61] op_sel_hi:[0,1,1]
	s_waitcnt vmcnt(3)
	v_pk_fma_f32 v[32:33], v[46:47], v[32:33], v[62:63] op_sel_hi:[0,1,1]
	v_pk_fma_f32 v[6:7], v[46:47], v[36:37], v[6:7] op_sel_hi:[0,1,1]
	v_pk_fma_f32 v[18:19], v[46:47], v[40:41], v[18:19] op_sel_hi:[0,1,1]
	v_pk_fma_f32 v[26:27], v[46:47], v[42:43], v[26:27] op_sel_hi:[0,1,1]
	s_waitcnt vmcnt(2)
	v_pk_fma_f32 v[0:1], v[24:25], v[0:1], v[32:33] op_sel_hi:[0,1,1]
	v_pk_fma_f32 v[6:7], v[24:25], v[8:9], v[6:7] op_sel_hi:[0,1,1]
	v_pk_fma_f32 v[8:9], v[24:25], v[12:13], v[18:19] op_sel_hi:[0,1,1]
	v_pk_fma_f32 v[12:13], v[24:25], v[20:21], v[26:27] op_sel_hi:[0,1,1]
	s_waitcnt vmcnt(1)
	v_pk_fma_f32 v[0:1], v[16:17], v[28:29], v[0:1] op_sel_hi:[0,1,1]
	v_pk_fma_f32 v[6:7], v[16:17], v[30:31], v[6:7] op_sel_hi:[0,1,1]
	v_pk_fma_f32 v[8:9], v[16:17], v[34:35], v[8:9] op_sel_hi:[0,1,1]
	v_pk_fma_f32 v[12:13], v[16:17], v[38:39], v[12:13] op_sel_hi:[0,1,1]
	s_waitcnt vmcnt(0)
	v_pk_fma_f32 v[62:63], v[4:5], v[2:3], v[0:1] op_sel_hi:[0,1,1]
	v_pk_fma_f32 v[60:61], v[4:5], v[10:11], v[6:7] op_sel_hi:[0,1,1]
	v_pk_fma_f32 v[58:59], v[4:5], v[14:15], v[8:9] op_sel_hi:[0,1,1]
	v_pk_fma_f32 v[16:17], v[4:5], v[22:23], v[12:13] op_sel_hi:[0,1,1]
	s_cbranch_scc0 .LBB0_408
	v_add_u32_e32 v0, s0, v50
	v_ashrrev_i32_e32 v1, 31, v0
	v_lshl_add_u64 v[0:1], v[0:1], 2, s[40:41]
	ds_write2st64_b32 v53, v63, v62 offset0:128 offset1:129
	ds_write2st64_b32 v53, v61, v60 offset0:130 offset1:131
	ds_write2st64_b32 v53, v59, v58 offset0:132 offset1:133
	ds_write2st64_b32 v53, v17, v16 offset0:134 offset1:135
	s_waitcnt lgkmcnt(0)
	s_barrier
	global_load_dword v10, v[0:1], off
	ds_read2st64_b32 v[0:1], v55 offset0:128 offset1:136
	ds_read2st64_b32 v[2:3], v55 offset0:144 offset1:152
	ds_read2st64_b32 v[4:5], v55 offset0:160 offset1:168
	ds_read2st64_b32 v[6:7], v55 offset0:176 offset1:184
	v_mad_i64_i32 v[8:9], s[24:25], s42, v52, 0
	v_lshl_add_u64 v[8:9], v[8:9], 2, s[38:39]
	s_add_i32 s46, s46, 64
	v_lshl_add_u64 v[8:9], s[0:1], 2, v[8:9]
	s_lshr_b32 vcc_lo, s46, 6
	s_cmp_lg_u32 vcc_lo, 4
	v_lshl_add_u64 v[8:9], v[8:9], 0, v[164:165]
	s_waitcnt vmcnt(0) lgkmcnt(3)
	v_add_f32_e32 v0, v10, v0
	v_add_f32_e32 v0, v0, v1
	s_waitcnt lgkmcnt(2)
	v_add_f32_e32 v0, v0, v2
	v_add_f32_e32 v0, v0, v3
	s_waitcnt lgkmcnt(1)
	v_add_f32_e32 v0, v0, v4
	v_add_f32_e32 v0, v0, v5
	s_waitcnt lgkmcnt(0)
	v_add_f32_e32 v0, v0, v6
	v_add_f32_e32 v0, v0, v7
	global_store_dword v[8:9], v0, off
	s_barrier
	s_cbranch_scc0 .LBB0_403
